# P3 QKV epilogue (3 units): bf16 row stores widened to dwordx4 via v_permlane16_swap, on top of P2/P5
# speedup vs baseline: 1.0296x; 1.0024x over previous
.LBB0_521:
	v_mbcnt_lo_u32_b32 v46, -1, 0
	v_mbcnt_hi_u32_b32 v46, -1, v46
	v_bfe_u32 v46, v46, 4, 1
	v_mul_u32_u24_e32 v46, 24, v46
	v_mov_b32_e32 v47, 0
	s_lshl_b32 s14, s70, 8
	s_or_b32 s14, s14, s57
	v_lshl_add_u32 v2, v159, 2, s14
	v_ashrrev_i32_e32 v3, 31, v2
	v_mov_b64_e32 v[0:1], s[52:53]
	v_mad_i64_i32 v[4:5], s[14:15], v158, s5, v[0:1]
	v_lshlrev_b64 v[2:3], 1, v[2:3]
	v_lshl_add_u64 v[4:5], v[4:5], 0, v[2:3]
	v_cvt_pk_bf16_f32 v28, v240, v241
	v_cvt_pk_bf16_f32 v29, v236, v237
	v_cvt_pk_bf16_f32 v30, v238, v239
	v_cvt_pk_bf16_f32 v31, v234, v235
	v_or_b32_e32 v8, 16, v158
	s_nop 1
	v_permlane16_swap_b32 v28, v30
	v_permlane16_swap_b32 v29, v31
	v_lshl_add_u64 v[44:45], v[4:5], 0, v[46:47]
	global_store_dwordx4 v[44:45], v[28:31], off
	v_cvt_pk_bf16_f32 v40, v232, v233
	v_cvt_pk_bf16_f32 v41, v226, v227
	v_cvt_pk_bf16_f32 v42, v230, v231
	v_cvt_pk_bf16_f32 v43, v228, v229
	s_nop 1
	v_permlane16_swap_b32 v40, v42
	v_permlane16_swap_b32 v41, v43
	v_lshl_add_u64 v[44:45], v[4:5], 0, v[46:47]
	global_store_dwordx4 v[44:45], v[40:43], off offset:256
	v_mad_i64_i32 v[4:5], s[14:15], v8, s5, v[0:1]
	v_lshl_add_u64 v[4:5], v[4:5], 0, v[2:3]
	v_cvt_pk_bf16_f32 v28, v222, v223
	v_cvt_pk_bf16_f32 v29, v218, v219
	v_cvt_pk_bf16_f32 v30, v220, v221
	v_cvt_pk_bf16_f32 v31, v216, v217
	v_or_b32_e32 v9, 32, v158
	s_nop 1
	v_permlane16_swap_b32 v28, v30
	v_permlane16_swap_b32 v29, v31
	v_lshl_add_u64 v[44:45], v[4:5], 0, v[46:47]
	global_store_dwordx4 v[44:45], v[28:31], off
	v_cvt_pk_bf16_f32 v40, v214, v215
	v_cvt_pk_bf16_f32 v41, v208, v209
	v_cvt_pk_bf16_f32 v42, v212, v213
	v_cvt_pk_bf16_f32 v43, v210, v211
	s_nop 1
	v_permlane16_swap_b32 v40, v42
	v_permlane16_swap_b32 v41, v43
	v_lshl_add_u64 v[44:45], v[4:5], 0, v[46:47]
	global_store_dwordx4 v[44:45], v[40:43], off offset:256
	v_mad_i64_i32 v[4:5], s[14:15], v9, s5, v[0:1]
	v_lshl_add_u64 v[4:5], v[4:5], 0, v[2:3]
	v_cvt_pk_bf16_f32 v28, v206, v207
	v_cvt_pk_bf16_f32 v29, v202, v203
	v_cvt_pk_bf16_f32 v30, v204, v205
	v_cvt_pk_bf16_f32 v31, v200, v201
	v_or_b32_e32 v10, 48, v158
	s_nop 1
	v_permlane16_swap_b32 v28, v30
	v_permlane16_swap_b32 v29, v31
	v_lshl_add_u64 v[44:45], v[4:5], 0, v[46:47]
	global_store_dwordx4 v[44:45], v[28:31], off
	v_cvt_pk_bf16_f32 v40, v94, v95
	v_cvt_pk_bf16_f32 v41, v88, v89
	v_cvt_pk_bf16_f32 v42, v90, v91
	v_cvt_pk_bf16_f32 v43, v92, v93
	s_nop 1
	v_permlane16_swap_b32 v40, v42
	v_permlane16_swap_b32 v41, v43
	v_lshl_add_u64 v[44:45], v[4:5], 0, v[46:47]
	global_store_dwordx4 v[44:45], v[40:43], off offset:256
	v_mad_i64_i32 v[4:5], s[14:15], v10, s5, v[0:1]
	v_lshl_add_u64 v[4:5], v[4:5], 0, v[2:3]
	v_cvt_pk_bf16_f32 v28, v102, v103
	v_cvt_pk_bf16_f32 v29, v96, v97
	v_cvt_pk_bf16_f32 v30, v98, v99
	v_cvt_pk_bf16_f32 v31, v100, v101
	v_add_u32_e32 v11, 0x80, v158
	s_nop 1
	v_permlane16_swap_b32 v28, v30
	v_permlane16_swap_b32 v29, v31
	v_lshl_add_u64 v[44:45], v[4:5], 0, v[46:47]
	global_store_dwordx4 v[44:45], v[28:31], off
	v_cvt_pk_bf16_f32 v40, v118, v119
	v_cvt_pk_bf16_f32 v41, v112, v113
	v_cvt_pk_bf16_f32 v42, v114, v115
	v_cvt_pk_bf16_f32 v43, v116, v117
	s_nop 1
	v_permlane16_swap_b32 v40, v42
	v_permlane16_swap_b32 v41, v43
	v_lshl_add_u64 v[44:45], v[4:5], 0, v[46:47]
	global_store_dwordx4 v[44:45], v[40:43], off offset:256
	v_mad_i64_i32 v[4:5], s[14:15], v11, s5, v[0:1]
	v_lshl_add_u64 v[4:5], v[4:5], 0, v[2:3]
	v_cvt_pk_bf16_f32 v28, v198, v199
	v_cvt_pk_bf16_f32 v29, v194, v195
	v_cvt_pk_bf16_f32 v30, v196, v197
	v_cvt_pk_bf16_f32 v31, v192, v193
	v_add_u32_e32 v12, 0x90, v158
	s_nop 1
	v_permlane16_swap_b32 v28, v30
	v_permlane16_swap_b32 v29, v31
	v_lshl_add_u64 v[44:45], v[4:5], 0, v[46:47]
	global_store_dwordx4 v[44:45], v[28:31], off
	v_cvt_pk_bf16_f32 v40, v126, v127
	v_cvt_pk_bf16_f32 v41, v120, v121
	v_cvt_pk_bf16_f32 v42, v122, v123
	v_cvt_pk_bf16_f32 v43, v124, v125
	s_nop 1
	v_permlane16_swap_b32 v40, v42
	v_permlane16_swap_b32 v41, v43
	v_lshl_add_u64 v[44:45], v[4:5], 0, v[46:47]
	global_store_dwordx4 v[44:45], v[40:43], off offset:256
	v_mad_i64_i32 v[4:5], s[14:15], v12, s5, v[0:1]
	v_lshl_add_u64 v[4:5], v[4:5], 0, v[2:3]
	v_cvt_pk_bf16_f32 v28, v190, v191
	v_cvt_pk_bf16_f32 v29, v186, v187
	v_cvt_pk_bf16_f32 v30, v188, v189
	v_cvt_pk_bf16_f32 v31, v184, v185
	v_add_u32_e32 v13, 0xa0, v158
	s_nop 1
	v_permlane16_swap_b32 v28, v30
	v_permlane16_swap_b32 v29, v31
	v_lshl_add_u64 v[44:45], v[4:5], 0, v[46:47]
	global_store_dwordx4 v[44:45], v[28:31], off
	v_cvt_pk_bf16_f32 v40, v134, v135
	v_cvt_pk_bf16_f32 v41, v128, v129
	v_cvt_pk_bf16_f32 v42, v130, v131
	v_cvt_pk_bf16_f32 v43, v132, v133
	s_nop 1
	v_permlane16_swap_b32 v40, v42
	v_permlane16_swap_b32 v41, v43
	v_lshl_add_u64 v[44:45], v[4:5], 0, v[46:47]
	global_store_dwordx4 v[44:45], v[40:43], off offset:256
	v_mad_i64_i32 v[4:5], s[14:15], v13, s5, v[0:1]
	v_lshl_add_u64 v[4:5], v[4:5], 0, v[2:3]
	v_cvt_pk_bf16_f32 v28, v182, v183
	v_cvt_pk_bf16_f32 v29, v178, v179
	v_add_u32_e32 v14, 0xb0, v158
	v_cvt_pk_bf16_f32 v30, v180, v181
	v_cvt_pk_bf16_f32 v31, v176, v177
	s_nop 1
	v_permlane16_swap_b32 v28, v30
	v_permlane16_swap_b32 v29, v31
	v_lshl_add_u64 v[44:45], v[4:5], 0, v[46:47]
	global_store_dwordx4 v[44:45], v[28:31], off
	v_cvt_pk_bf16_f32 v40, v142, v143
	v_cvt_pk_bf16_f32 v41, v136, v137
	v_mad_i64_i32 v[0:1], s[14:15], v14, s5, v[0:1]
	v_cvt_pk_bf16_f32 v42, v138, v139
	v_cvt_pk_bf16_f32 v43, v140, v141
	s_nop 1
	v_permlane16_swap_b32 v40, v42
	v_permlane16_swap_b32 v41, v43
	v_lshl_add_u64 v[44:45], v[4:5], 0, v[46:47]
	global_store_dwordx4 v[44:45], v[40:43], off offset:256
	v_lshl_add_u64 v[0:1], v[0:1], 0, v[2:3]
	v_cvt_pk_bf16_f32 v28, v166, v167
	v_cvt_pk_bf16_f32 v29, v162, v163
	v_cvt_pk_bf16_f32 v30, v164, v165
	v_cvt_pk_bf16_f32 v31, v160, v161
	s_nop 1
	v_permlane16_swap_b32 v28, v30
	v_permlane16_swap_b32 v29, v31
	v_lshl_add_u64 v[44:45], v[0:1], 0, v[46:47]
	global_store_dwordx4 v[44:45], v[28:31], off
	v_cvt_pk_bf16_f32 v40, v172, v173
	v_cvt_pk_bf16_f32 v41, v170, v171
	s_andn2_b64 vcc, exec, s[12:13]
	s_mov_b64 s[12:13], -1
	v_cvt_pk_bf16_f32 v42, v174, v175
	v_cvt_pk_bf16_f32 v43, v168, v169
	s_nop 1
	v_permlane16_swap_b32 v40, v42
	v_permlane16_swap_b32 v41, v43
	v_lshl_add_u64 v[44:45], v[0:1], 0, v[46:47]
	global_store_dwordx4 v[44:45], v[40:43], off offset:256
	s_cbranch_vccnz .LBB0_344
	s_and_b64 vcc, exec, s[6:7]
	s_cbranch_vccnz .LBB0_343
	s_barrier
	s_branch .LBB0_343
